# hyena Toeplitz F-table LDS row stride 0x2020->0x2040 (conflict-free ds_read_b128 fragment reads), other hyena LDS tables shifted +256B
# speedup vs baseline: 1.0046x; 1.0030x over previous
.LBB0_792:
	s_or_b64 exec, exec, s[6:7]
	s_waitcnt vmcnt(0)
	v_or_b32_e32 v191, v39, v52
	v_and_b32_e32 v39, 0xff0, v36
	s_add_i32 s2, 0, 0x10200
	s_add_i32 s13, 0, 0x18280
	v_or_b32_e32 v196, v43, v42
	v_add_u32_e32 v145, s2, v39
	v_add_u32_e32 v163, s13, v39
	v_bfe_u32 v39, v144, 3, 1
	v_mul_u32_u24_e32 v43, 0x204, v46
	v_or_b32_e32 v195, v37, v47
	v_bfe_u32 v37, v144, 4, 2
	v_lshrrev_b32_e32 v44, 2, v144
	v_or_b32_e32 v43, v43, v39
	v_cmp_eq_u32_e64 s[6:7], 0, v39
	v_and_b32_e32 v39, 8, v144
	v_and_b32_e32 v44, 0xf0, v44
	v_sub_u32_e32 v45, v43, v37
	v_mov_b32_e32 v47, 0x800
	v_cmp_ne_u32_e64 s[8:9], 0, v39
	s_movk_i32 s12, 0x1010
	v_add_u32_e32 v44, v45, v44
	v_mov_b32_e32 v45, 0x1800
	v_cndmask_b32_e64 v164, v47, 0, s[8:9]
	v_mov_b32_e32 v47, s2
	v_or_b32_e32 v190, v41, v40
	v_lshrrev_b32_e32 v40, 6, v144
	v_lshrrev_b32_e32 v41, 8, v144
	v_lshl_add_u32 v44, v44, 4, v45
	v_lshlrev_b32_e32 v45, 4, v37
	v_mad_u32_u24 v165, v46, s12, v47
	v_lshlrev_b32_e32 v47, 3, v37
	v_mov_b32_e32 v37, s13
	v_mov_b32_e32 v129, 0
	v_mul_u32_u24_e32 v160, 0x1010, v41
	v_add_u32_e32 v41, 0x200, v144
	v_add_lshl_u32 v39, v40, v39, 8
	v_mad_u32_u24 v167, v46, s12, v37
	v_mov_b32_e32 v37, v129
	v_or_b32_e32 v194, v131, v48
	v_lshrrev_b32_e32 v41, 8, v41
	v_or_b32_e32 v134, v39, v47
	v_add_u32_e32 v48, v165, v39
	v_mov_b32_e32 v39, v129
	v_lshl_add_u64 v[138:139], s[16:17], 0, v[36:37]
	v_lshlrev_b32_e32 v37, 4, v43
	v_mul_u32_u24_e32 v161, 0x1010, v41
	v_add_u32_e32 v41, 0x600, v144
	v_lshl_add_u64 v[136:137], s[18:19], 0, v[38:39]
	v_lshlrev_b32_e32 v38, 12, v46
	v_lshl_add_u32 v37, v40, 8, v37
	v_lshrrev_b32_e32 v41, 8, v41
	v_lshl_add_u64 v[38:39], s[22:23], 0, v[38:39]
	v_mov_b32_e32 v135, v129
	v_sub_u32_e32 v37, v37, v45
	v_mul_u32_u24_e32 v162, 0x1010, v41
	v_sub_u32_e32 v41, 0x1ff0, v36
	v_sub_u32_e32 v42, 0x2000, v36
	v_lshl_add_u64 v[38:39], v[38:39], 0, v[134:135]
	s_mov_b64 s[12:13], 0x12a00000
	v_add_u32_e32 v37, 0, v37
	v_add_u32_e32 v175, 0, v36
	s_add_i32 s2, 0, 0x20300
	v_or_b32_e32 v189, v54, v53
	v_or_b32_e32 v192, v133, v51
	v_or_b32_e32 v193, v50, v49
	s_mov_b32 s15, 0
	v_add_u32_e32 v166, v165, v45
	v_or_b32_e32 v168, 32, v134
	v_or_b32_e32 v169, 64, v134
	v_or_b32_e32 v170, 0x60, v134
	v_or_b32_e32 v171, 0x80, v134
	v_or_b32_e32 v172, 0xa0, v134
	v_or_b32_e32 v173, 0xc0, v134
	v_or_b32_e32 v174, 0xe0, v134
	v_lshl_add_u64 v[140:141], v[38:39], 0, s[12:13]
	v_add_u32_e32 v135, 0x1700, v37
	v_add_u32_e32 v176, 0x20300, v175
	s_waitcnt lgkmcnt(0)
	s_add_i32 s46, 0, 0x22300
	v_mov_b32_e32 v177, 0x3000
	v_mov_b32_e32 v178, 0x6000
	v_mov_b32_e32 v179, 0x1000
	v_mov_b32_e32 v180, 0x4000
	v_mov_b32_e32 v181, 0x7000
	s_mov_b32 s47, 0x1000706
	s_mov_b64 s[16:17], 0x4000000
	v_add_u32_e32 v182, v48, v47
	v_mov_b32_e32 v183, 0x2000
	v_mov_b32_e32 v184, 0x5000
	v_mov_b32_e32 v185, 0x8000
	s_mov_b64 s[18:19], 0x1c00000
	v_mov_b32_e32 v200, v129
	v_mov_b32_e32 v201, v129
	v_mov_b32_e32 v202, v129
	v_mov_b32_e32 v203, v129
	v_add_u32_e32 v186, s2, v41
	v_add_u32_e32 v187, s2, v42
	v_add_u32_e32 v188, 0, v44
	s_branch .LBB0_794

.LBB0_794:
	ds_write_b128 v176, v[0:3]
	s_and_saveexec_b64 s[28:29], s[4:5]
	v_mov_b32_e32 v36, s46
	ds_write_b128 v36, v[200:203]
	s_or_b64 exec, exec, s[28:29]
	s_add_i32 s34, s15, s14
	v_readlane_b32 s56, v248, 8
	s_ashr_i32 s35, s34, 31
	v_readlane_b32 s57, v248, 9
	s_lshl_b64 s[42:43], s[34:35], 2
	v_readlane_b32 s58, v248, 10
	v_readlane_b32 s59, v248, 11
	s_mov_b64 s[48:49], s[56:57]
	s_add_u32 s36, s48, s42
	s_mov_b64 s[50:51], s[58:59]
	s_addc_u32 s37, s49, s43
	s_add_u32 s40, s50, s42
	global_load_dword v38, v177, s[36:37]
	global_load_dword v40, v129, s[36:37]
	global_load_dword v36, v178, s[36:37]
	s_addc_u32 s41, s51, s43
	global_load_dword v42, v129, s[40:41]
	v_and_b32_e32 v46, 0xffff0000, v5
	v_and_b32_e32 v48, 0xffff0000, v4
	v_and_b32_e32 v66, 0xffff0000, v9
	v_and_b32_e32 v45, 16, v7
	v_and_b32_e32 v44, 0xffff0000, v6
	v_and_b32_e32 v47, 16, v6
	v_lshlrev_b32_e32 v57, 16, v6
	v_and_b32_e32 v49, 16, v5
	v_lshlrev_b32_e32 v59, 16, v5
	v_lshlrev_b32_e32 v61, 16, v4
	v_lshlrev_b32_e32 v60, 16, v195
	v_and_b32_e32 v51, 16, v11
	v_and_b32_e32 v50, 0xffff0000, v10
	v_lshlrev_b32_e32 v69, 16, v10
	v_mov_b32_e32 v56, v46
	v_mov_b32_e32 v58, v48
	v_mov_b32_e32 v68, v66
	v_mov_b32_e32 v52, v44
	v_pk_mov_b32 v[76:77], v[60:61], v[48:49] op_sel:[1,0]
	v_mov_b32_e32 v62, v50
	v_pk_mov_b32 v[80:81], v[58:59], v[46:47] op_sel:[1,0]
	v_pk_mov_b32 v[82:83], v[56:57], v[44:45] op_sel:[1,0]
	v_pk_mov_b32 v[86:87], v[68:69], v[50:51] op_sel:[1,0]
	global_load_dword v48, v180, s[36:37]
	global_load_dword v44, v181, s[36:37]
	global_load_dword v50, v179, s[36:37]
	global_load_dword v46, v179, s[40:41]
	v_lshlrev_b32_e32 v53, 16, v7
	v_and_b32_e32 v55, 0xffff0000, v195
	v_and_b32_e32 v54, 0xffff0000, v7
	v_and_b32_e32 v70, 0xffff0000, v8
	v_and_b32_e32 v67, 16, v10
	v_and_b32_e32 v71, 16, v9
	v_lshlrev_b32_e32 v73, 16, v9
	v_lshlrev_b32_e32 v75, 16, v8
	v_lshlrev_b32_e32 v74, 16, v194
	v_mov_b32_e32 v72, v70
	v_pk_mov_b32 v[78:79], v[52:53], v[54:55] op_sel:[1,0]
	v_pk_mov_b32 v[70:71], v[74:75], v[70:71] op_sel:[1,0]
	v_pk_mov_b32 v[66:67], v[72:73], v[66:67] op_sel:[1,0]
	v_add_u32_e32 v37, v145, v160
	v_lshlrev_b32_e32 v63, 16, v11
	v_and_b32_e32 v65, 0xffff0000, v194
	v_and_b32_e32 v64, 0xffff0000, v11
	v_pk_mov_b32 v[84:85], v[62:63], v[64:65] op_sel:[1,0]
	v_add_u32_e32 v142, v163, v160
	v_add_u32_e32 v148, v163, v161
	v_add_u32_e32 v199, v163, v162
	s_lshl_b64 s[30:31], s[34:35], 15
	v_mov_b32_e32 v147, 0
	v_mov_b32_e32 v153, 0
	v_readlane_b32 s60, v248, 12
	v_readlane_b32 s61, v248, 13
	v_readlane_b32 s62, v248, 14
	v_readlane_b32 s63, v248, 15
	v_readlane_b32 s64, v248, 16
	v_readlane_b32 s65, v248, 17
	v_readlane_b32 s66, v248, 18
	v_readlane_b32 s67, v248, 19
	v_readlane_b32 s68, v248, 20
	v_readlane_b32 s69, v248, 21
	v_readlane_b32 s70, v248, 22
	v_readlane_b32 s71, v248, 23
	s_waitcnt vmcnt(7)
	v_pk_mul_f32 v[76:77], v[38:39], v[76:77] op_sel_hi:[0,1]
	v_pk_mul_f32 v[80:81], v[38:39], v[80:81] op_sel_hi:[0,1]
	v_pk_mul_f32 v[82:83], v[38:39], v[82:83] op_sel_hi:[0,1]
	v_pk_mul_f32 v[78:79], v[38:39], v[78:79] op_sel_hi:[0,1]
	v_pk_mul_f32 v[70:71], v[38:39], v[70:71] op_sel_hi:[0,1]
	v_pk_mul_f32 v[66:67], v[38:39], v[66:67] op_sel_hi:[0,1]
	s_waitcnt vmcnt(6)
	v_pk_fma_f32 v[60:61], v[40:41], v[60:61], v[76:77] op_sel_hi:[0,1,1]
	v_pk_fma_f32 v[76:77], v[40:41], v[58:59], v[80:81] op_sel_hi:[0,1,1]
	v_pk_fma_f32 v[80:81], v[40:41], v[56:57], v[82:83] op_sel_hi:[0,1,1]
	v_pk_fma_f32 v[78:79], v[40:41], v[52:53], v[78:79] op_sel_hi:[0,1,1]
	v_pk_mul_f32 v[86:87], v[38:39], v[86:87] op_sel_hi:[0,1]
	v_pk_fma_f32 v[70:71], v[40:41], v[74:75], v[70:71] op_sel_hi:[0,1,1]
	v_pk_fma_f32 v[66:67], v[40:41], v[72:73], v[66:67] op_sel_hi:[0,1,1]
	s_waitcnt vmcnt(5)
	v_pk_fma_f32 v[58:59], v[36:37], v[58:59], v[60:61] op_sel_hi:[0,1,1]
	v_pk_fma_f32 v[56:57], v[36:37], v[56:57], v[76:77] op_sel_hi:[0,1,1]
	v_pk_fma_f32 v[52:53], v[36:37], v[52:53], v[80:81] op_sel_hi:[0,1,1]
	v_pk_fma_f32 v[54:55], v[36:37], v[54:55], v[78:79] op_sel_hi:[0,1,1]
	v_pk_mul_f32 v[84:85], v[38:39], v[84:85] op_sel_hi:[0,1]
	v_pk_fma_f32 v[74:75], v[40:41], v[68:69], v[86:87] op_sel_hi:[0,1,1]
	v_pk_fma_f32 v[60:61], v[36:37], v[72:73], v[70:71] op_sel_hi:[0,1,1]
	v_pk_fma_f32 v[66:67], v[36:37], v[68:69], v[66:67] op_sel_hi:[0,1,1]
	s_waitcnt vmcnt(4)
	v_pk_add_f32 v[58:59], v[42:43], v[58:59] op_sel_hi:[0,1]
	v_pk_add_f32 v[56:57], v[42:43], v[56:57] op_sel_hi:[0,1]
	v_pk_add_f32 v[68:69], v[42:43], v[52:53] op_sel_hi:[0,1]
	v_pk_add_f32 v[70:71], v[42:43], v[54:55] op_sel_hi:[0,1]
	v_pk_fma_f32 v[82:83], v[40:41], v[62:63], v[84:85] op_sel_hi:[0,1,1]
	v_cvt_pk_bf16_f32 v52, v58, v59
	v_cvt_pk_bf16_f32 v53, v56, v57
	v_cvt_pk_bf16_f32 v54, v68, v69
	v_cvt_pk_bf16_f32 v55, v70, v71
	v_pk_fma_f32 v[62:63], v[36:37], v[62:63], v[74:75] op_sel_hi:[0,1,1]
	ds_write_b128 v37, v[52:55]
	v_pk_fma_f32 v[52:53], v[36:37], v[64:65], v[82:83] op_sel_hi:[0,1,1]
	v_pk_add_f32 v[60:61], v[42:43], v[60:61] op_sel_hi:[0,1]
	v_pk_add_f32 v[66:67], v[42:43], v[66:67] op_sel_hi:[0,1]
	v_pk_add_f32 v[62:63], v[42:43], v[62:63] op_sel_hi:[0,1]
	v_pk_add_f32 v[56:57], v[42:43], v[52:53] op_sel_hi:[0,1]
	v_cvt_pk_bf16_f32 v52, v60, v61
	v_cvt_pk_bf16_f32 v53, v66, v67
	v_cvt_pk_bf16_f32 v54, v62, v63
	v_cvt_pk_bf16_f32 v55, v56, v57
	v_add_u32_e32 v39, v145, v161
	v_and_b32_e32 v60, 0xffff0000, v13
	ds_write_b128 v39, v[52:55]
	v_and_b32_e32 v53, 16, v15
	v_and_b32_e32 v52, 0xffff0000, v14
	v_lshlrev_b32_e32 v63, 16, v14
	v_mov_b32_e32 v62, v60
	v_and_b32_e32 v64, 0xffff0000, v12
	v_mov_b32_e32 v54, v52
	v_and_b32_e32 v61, 16, v14
	v_lshlrev_b32_e32 v67, 16, v13
	v_mov_b32_e32 v66, v64
	v_pk_mov_b32 v[52:53], v[62:63], v[52:53] op_sel:[1,0]
	v_pk_mov_b32 v[60:61], v[66:67], v[60:61] op_sel:[1,0]
	v_pk_mul_f32 v[52:53], v[38:39], v[52:53] op_sel_hi:[0,1]
	v_lshlrev_b32_e32 v55, 16, v15
	v_and_b32_e32 v57, 0xffff0000, v193
	v_and_b32_e32 v56, 0xffff0000, v15
	v_and_b32_e32 v65, 16, v13
	v_lshlrev_b32_e32 v69, 16, v12
	v_lshlrev_b32_e32 v68, 16, v193
	v_pk_mul_f32 v[60:61], v[38:39], v[60:61] op_sel_hi:[0,1]
	v_pk_fma_f32 v[52:53], v[40:41], v[62:63], v[52:53] op_sel_hi:[0,1,1]
	v_pk_mov_b32 v[58:59], v[54:55], v[56:57] op_sel:[1,0]
	v_pk_mov_b32 v[64:65], v[68:69], v[64:65] op_sel:[1,0]
	v_pk_fma_f32 v[60:61], v[40:41], v[66:67], v[60:61] op_sel_hi:[0,1,1]
	v_pk_fma_f32 v[52:53], v[36:37], v[54:55], v[52:53] op_sel_hi:[0,1,1]
	v_pk_mul_f32 v[64:65], v[38:39], v[64:65] op_sel_hi:[0,1]
	v_pk_fma_f32 v[60:61], v[36:37], v[62:63], v[60:61] op_sel_hi:[0,1,1]
	v_pk_add_f32 v[62:63], v[42:43], v[52:53] op_sel_hi:[0,1]
	v_pk_mul_f32 v[52:53], v[38:39], v[58:59] op_sel_hi:[0,1]
	v_pk_fma_f32 v[64:65], v[40:41], v[68:69], v[64:65] op_sel_hi:[0,1,1]
	v_pk_fma_f32 v[52:53], v[40:41], v[54:55], v[52:53] op_sel_hi:[0,1,1]
	v_pk_fma_f32 v[64:65], v[36:37], v[66:67], v[64:65] op_sel_hi:[0,1,1]
	v_pk_fma_f32 v[52:53], v[36:37], v[56:57], v[52:53] op_sel_hi:[0,1,1]
	v_pk_add_f32 v[64:65], v[42:43], v[64:65] op_sel_hi:[0,1]
	v_pk_add_f32 v[60:61], v[42:43], v[60:61] op_sel_hi:[0,1]
	v_pk_add_f32 v[56:57], v[42:43], v[52:53] op_sel_hi:[0,1]
	v_cvt_pk_bf16_f32 v52, v64, v65
	v_cvt_pk_bf16_f32 v53, v60, v61
	v_cvt_pk_bf16_f32 v54, v62, v63
	v_cvt_pk_bf16_f32 v55, v56, v57
	ds_write_b128 v37, v[52:55] offset:16448
	v_and_b32_e32 v52, 0xffff0000, v18
	v_and_b32_e32 v60, 0xffff0000, v17
	v_and_b32_e32 v64, 0xffff0000, v16
	v_and_b32_e32 v53, 16, v19
	v_lshlrev_b32_e32 v55, 16, v19
	v_mov_b32_e32 v54, v52
	v_and_b32_e32 v57, 0xffff0000, v192
	v_and_b32_e32 v56, 0xffff0000, v19
	v_and_b32_e32 v61, 16, v18
	v_lshlrev_b32_e32 v63, 16, v18
	v_mov_b32_e32 v62, v60
	v_and_b32_e32 v65, 16, v17
	v_lshlrev_b32_e32 v67, 16, v17
	v_mov_b32_e32 v66, v64
	v_lshlrev_b32_e32 v69, 16, v16
	v_lshlrev_b32_e32 v68, 16, v192
	v_pk_mov_b32 v[58:59], v[54:55], v[56:57] op_sel:[1,0]
	v_pk_mov_b32 v[64:65], v[68:69], v[64:65] op_sel:[1,0]
	v_pk_mov_b32 v[60:61], v[66:67], v[60:61] op_sel:[1,0]
	v_pk_mov_b32 v[52:53], v[62:63], v[52:53] op_sel:[1,0]
	v_pk_mul_f32 v[64:65], v[38:39], v[64:65] op_sel_hi:[0,1]
	v_pk_mul_f32 v[60:61], v[38:39], v[60:61] op_sel_hi:[0,1]
	v_pk_mul_f32 v[52:53], v[38:39], v[52:53] op_sel_hi:[0,1]
	v_pk_mul_f32 v[38:39], v[38:39], v[58:59] op_sel_hi:[0,1]
	v_pk_fma_f32 v[64:65], v[40:41], v[68:69], v[64:65] op_sel_hi:[0,1,1]
	v_pk_fma_f32 v[60:61], v[40:41], v[66:67], v[60:61] op_sel_hi:[0,1,1]
	v_pk_fma_f32 v[52:53], v[40:41], v[62:63], v[52:53] op_sel_hi:[0,1,1]
	v_pk_fma_f32 v[38:39], v[40:41], v[54:55], v[38:39] op_sel_hi:[0,1,1]
	v_pk_fma_f32 v[64:65], v[36:37], v[66:67], v[64:65] op_sel_hi:[0,1,1]
	v_pk_fma_f32 v[60:61], v[36:37], v[62:63], v[60:61] op_sel_hi:[0,1,1]
	v_pk_fma_f32 v[52:53], v[36:37], v[54:55], v[52:53] op_sel_hi:[0,1,1]
	v_pk_fma_f32 v[36:37], v[36:37], v[56:57], v[38:39] op_sel_hi:[0,1,1]
	v_pk_add_f32 v[64:65], v[42:43], v[64:65] op_sel_hi:[0,1]
	v_pk_add_f32 v[60:61], v[42:43], v[60:61] op_sel_hi:[0,1]
	v_pk_add_f32 v[52:53], v[42:43], v[52:53] op_sel_hi:[0,1]
	v_pk_add_f32 v[40:41], v[42:43], v[36:37] op_sel_hi:[0,1]
	v_cvt_pk_bf16_f32 v36, v64, v65
	v_cvt_pk_bf16_f32 v37, v60, v61
	v_cvt_pk_bf16_f32 v38, v52, v53
	v_cvt_pk_bf16_f32 v39, v40, v41
	v_add_u32_e32 v40, v145, v162
	v_and_b32_e32 v52, 0xffff0000, v21
	ds_write_b128 v40, v[36:39]
	v_and_b32_e32 v37, 16, v23
	v_and_b32_e32 v36, 0xffff0000, v22
	v_lshlrev_b32_e32 v55, 16, v22
	v_mov_b32_e32 v54, v52
	v_and_b32_e32 v56, 0xffff0000, v20
	v_mov_b32_e32 v38, v36
	v_and_b32_e32 v53, 16, v22
	v_lshlrev_b32_e32 v59, 16, v21
	v_mov_b32_e32 v58, v56
	v_pk_mov_b32 v[36:37], v[54:55], v[36:37] op_sel:[1,0]
	v_pk_mov_b32 v[52:53], v[58:59], v[52:53] op_sel:[1,0]
	s_waitcnt vmcnt(3)
	v_pk_mul_f32 v[36:37], v[48:49], v[36:37] op_sel_hi:[0,1]
	v_lshlrev_b32_e32 v39, 16, v23
	v_and_b32_e32 v41, 0xffff0000, v191
	v_and_b32_e32 v40, 0xffff0000, v23
	v_and_b32_e32 v57, 16, v21
	v_lshlrev_b32_e32 v61, 16, v20
	v_lshlrev_b32_e32 v60, 16, v191
	v_pk_mul_f32 v[52:53], v[48:49], v[52:53] op_sel_hi:[0,1]
	s_waitcnt vmcnt(1)
	v_pk_fma_f32 v[36:37], v[50:51], v[54:55], v[36:37] op_sel_hi:[0,1,1]
	v_pk_mov_b32 v[42:43], v[38:39], v[40:41] op_sel:[1,0]
	v_pk_mov_b32 v[56:57], v[60:61], v[56:57] op_sel:[1,0]
	v_pk_fma_f32 v[52:53], v[50:51], v[58:59], v[52:53] op_sel_hi:[0,1,1]
	v_pk_fma_f32 v[36:37], v[44:45], v[38:39], v[36:37] op_sel_hi:[0,1,1]
	v_pk_mul_f32 v[56:57], v[48:49], v[56:57] op_sel_hi:[0,1]
	v_pk_fma_f32 v[52:53], v[44:45], v[54:55], v[52:53] op_sel_hi:[0,1,1]
	s_waitcnt vmcnt(0)
	v_pk_add_f32 v[54:55], v[46:47], v[36:37] op_sel_hi:[0,1]
	v_pk_mul_f32 v[36:37], v[48:49], v[42:43] op_sel_hi:[0,1]
	v_pk_fma_f32 v[56:57], v[50:51], v[60:61], v[56:57] op_sel_hi:[0,1,1]
	v_pk_fma_f32 v[36:37], v[50:51], v[38:39], v[36:37] op_sel_hi:[0,1,1]
	v_pk_fma_f32 v[56:57], v[44:45], v[58:59], v[56:57] op_sel_hi:[0,1,1]
	v_pk_fma_f32 v[36:37], v[44:45], v[40:41], v[36:37] op_sel_hi:[0,1,1]
	v_pk_add_f32 v[56:57], v[46:47], v[56:57] op_sel_hi:[0,1]
	v_pk_add_f32 v[52:53], v[46:47], v[52:53] op_sel_hi:[0,1]
	v_pk_add_f32 v[40:41], v[46:47], v[36:37] op_sel_hi:[0,1]
	v_cvt_pk_bf16_f32 v36, v56, v57
	v_cvt_pk_bf16_f32 v37, v52, v53
	v_cvt_pk_bf16_f32 v38, v54, v55
	v_cvt_pk_bf16_f32 v39, v40, v41
	v_and_b32_e32 v52, 0xffff0000, v25
	ds_write_b128 v142, v[36:39]
	v_and_b32_e32 v37, 16, v27
	v_and_b32_e32 v36, 0xffff0000, v26
	v_lshlrev_b32_e32 v55, 16, v26
	v_mov_b32_e32 v54, v52
	v_and_b32_e32 v56, 0xffff0000, v24
	v_mov_b32_e32 v38, v36
	v_and_b32_e32 v53, 16, v26
	v_lshlrev_b32_e32 v59, 16, v25
	v_mov_b32_e32 v58, v56
	v_pk_mov_b32 v[36:37], v[54:55], v[36:37] op_sel:[1,0]
	v_pk_mov_b32 v[52:53], v[58:59], v[52:53] op_sel:[1,0]
	v_pk_mul_f32 v[36:37], v[48:49], v[36:37] op_sel_hi:[0,1]
	v_lshlrev_b32_e32 v39, 16, v27
	v_and_b32_e32 v41, 0xffff0000, v190
	v_and_b32_e32 v40, 0xffff0000, v27
	v_and_b32_e32 v57, 16, v25
	v_lshlrev_b32_e32 v61, 16, v24
	v_lshlrev_b32_e32 v60, 16, v190
	v_pk_mul_f32 v[52:53], v[48:49], v[52:53] op_sel_hi:[0,1]
	v_pk_fma_f32 v[36:37], v[50:51], v[54:55], v[36:37] op_sel_hi:[0,1,1]
	v_pk_mov_b32 v[42:43], v[38:39], v[40:41] op_sel:[1,0]
	v_pk_mov_b32 v[56:57], v[60:61], v[56:57] op_sel:[1,0]
	v_pk_fma_f32 v[52:53], v[50:51], v[58:59], v[52:53] op_sel_hi:[0,1,1]
	v_pk_fma_f32 v[36:37], v[44:45], v[38:39], v[36:37] op_sel_hi:[0,1,1]
	v_pk_mul_f32 v[56:57], v[48:49], v[56:57] op_sel_hi:[0,1]
	v_pk_fma_f32 v[52:53], v[44:45], v[54:55], v[52:53] op_sel_hi:[0,1,1]
	v_pk_add_f32 v[54:55], v[46:47], v[36:37] op_sel_hi:[0,1]
	v_pk_mul_f32 v[36:37], v[48:49], v[42:43] op_sel_hi:[0,1]
	v_pk_fma_f32 v[56:57], v[50:51], v[60:61], v[56:57] op_sel_hi:[0,1,1]
	v_pk_fma_f32 v[36:37], v[50:51], v[38:39], v[36:37] op_sel_hi:[0,1,1]
	v_pk_fma_f32 v[56:57], v[44:45], v[58:59], v[56:57] op_sel_hi:[0,1,1]
	v_pk_fma_f32 v[36:37], v[44:45], v[40:41], v[36:37] op_sel_hi:[0,1,1]
	v_pk_add_f32 v[56:57], v[46:47], v[56:57] op_sel_hi:[0,1]
	v_pk_add_f32 v[52:53], v[46:47], v[52:53] op_sel_hi:[0,1]
	v_pk_add_f32 v[40:41], v[46:47], v[36:37] op_sel_hi:[0,1]
	v_cvt_pk_bf16_f32 v36, v56, v57
	v_cvt_pk_bf16_f32 v37, v52, v53
	v_cvt_pk_bf16_f32 v38, v54, v55
	v_cvt_pk_bf16_f32 v39, v40, v41
	v_and_b32_e32 v52, 0xffff0000, v29
	ds_write_b128 v148, v[36:39]
	v_and_b32_e32 v37, 16, v31
	v_and_b32_e32 v36, 0xffff0000, v30
	v_lshlrev_b32_e32 v55, 16, v30
	v_mov_b32_e32 v54, v52
	v_and_b32_e32 v56, 0xffff0000, v28
	v_mov_b32_e32 v38, v36
	v_and_b32_e32 v53, 16, v30
	v_lshlrev_b32_e32 v59, 16, v29
	v_mov_b32_e32 v58, v56
	v_pk_mov_b32 v[36:37], v[54:55], v[36:37] op_sel:[1,0]
	v_pk_mov_b32 v[52:53], v[58:59], v[52:53] op_sel:[1,0]
	v_pk_mul_f32 v[36:37], v[48:49], v[36:37] op_sel_hi:[0,1]
	v_lshlrev_b32_e32 v39, 16, v31
	v_and_b32_e32 v41, 0xffff0000, v189
	v_and_b32_e32 v40, 0xffff0000, v31
	v_and_b32_e32 v57, 16, v29
	v_lshlrev_b32_e32 v61, 16, v28
	v_lshlrev_b32_e32 v60, 16, v189
	v_pk_mul_f32 v[52:53], v[48:49], v[52:53] op_sel_hi:[0,1]
	v_pk_fma_f32 v[36:37], v[50:51], v[54:55], v[36:37] op_sel_hi:[0,1,1]
	v_pk_mov_b32 v[42:43], v[38:39], v[40:41] op_sel:[1,0]
	v_pk_mov_b32 v[56:57], v[60:61], v[56:57] op_sel:[1,0]
	v_pk_fma_f32 v[52:53], v[50:51], v[58:59], v[52:53] op_sel_hi:[0,1,1]
	v_pk_fma_f32 v[36:37], v[44:45], v[38:39], v[36:37] op_sel_hi:[0,1,1]
	v_pk_mul_f32 v[56:57], v[48:49], v[56:57] op_sel_hi:[0,1]
	v_pk_fma_f32 v[52:53], v[44:45], v[54:55], v[52:53] op_sel_hi:[0,1,1]
	v_pk_add_f32 v[54:55], v[46:47], v[36:37] op_sel_hi:[0,1]
	v_pk_mul_f32 v[36:37], v[48:49], v[42:43] op_sel_hi:[0,1]
	v_pk_fma_f32 v[56:57], v[50:51], v[60:61], v[56:57] op_sel_hi:[0,1,1]
	v_pk_fma_f32 v[36:37], v[50:51], v[38:39], v[36:37] op_sel_hi:[0,1,1]
	v_pk_fma_f32 v[56:57], v[44:45], v[58:59], v[56:57] op_sel_hi:[0,1,1]
	v_pk_fma_f32 v[36:37], v[44:45], v[40:41], v[36:37] op_sel_hi:[0,1,1]
	v_pk_add_f32 v[56:57], v[46:47], v[56:57] op_sel_hi:[0,1]
	v_pk_add_f32 v[52:53], v[46:47], v[52:53] op_sel_hi:[0,1]
	v_pk_add_f32 v[40:41], v[46:47], v[36:37] op_sel_hi:[0,1]
	v_cvt_pk_bf16_f32 v36, v56, v57
	v_cvt_pk_bf16_f32 v37, v52, v53
	v_cvt_pk_bf16_f32 v38, v54, v55
	v_cvt_pk_bf16_f32 v39, v40, v41
	v_and_b32_e32 v52, 0xffff0000, v33
	ds_write_b128 v142, v[36:39] offset:16448
	v_and_b32_e32 v37, 16, v35
	v_and_b32_e32 v36, 0xffff0000, v34
	v_lshlrev_b32_e32 v55, 16, v34
	v_mov_b32_e32 v54, v52
	v_and_b32_e32 v56, 0xffff0000, v32
	v_mov_b32_e32 v38, v36
	v_and_b32_e32 v53, 16, v34
	v_lshlrev_b32_e32 v59, 16, v33
	v_mov_b32_e32 v58, v56
	v_pk_mov_b32 v[36:37], v[54:55], v[36:37] op_sel:[1,0]
	v_pk_mov_b32 v[52:53], v[58:59], v[52:53] op_sel:[1,0]
	v_pk_mul_f32 v[36:37], v[48:49], v[36:37] op_sel_hi:[0,1]
	v_lshlrev_b32_e32 v39, 16, v35
	v_and_b32_e32 v41, 0xffff0000, v196
	v_and_b32_e32 v40, 0xffff0000, v35
	v_and_b32_e32 v57, 16, v33
	v_lshlrev_b32_e32 v61, 16, v32
	v_lshlrev_b32_e32 v60, 16, v196
	v_pk_mul_f32 v[52:53], v[48:49], v[52:53] op_sel_hi:[0,1]
	v_pk_fma_f32 v[36:37], v[50:51], v[54:55], v[36:37] op_sel_hi:[0,1,1]
	v_pk_mov_b32 v[42:43], v[38:39], v[40:41] op_sel:[1,0]
	v_pk_mov_b32 v[56:57], v[60:61], v[56:57] op_sel:[1,0]
	v_pk_fma_f32 v[52:53], v[50:51], v[58:59], v[52:53] op_sel_hi:[0,1,1]
	v_pk_fma_f32 v[36:37], v[44:45], v[38:39], v[36:37] op_sel_hi:[0,1,1]
	v_pk_mul_f32 v[56:57], v[48:49], v[56:57] op_sel_hi:[0,1]
	v_pk_fma_f32 v[52:53], v[44:45], v[54:55], v[52:53] op_sel_hi:[0,1,1]
	v_pk_add_f32 v[54:55], v[46:47], v[36:37] op_sel_hi:[0,1]
	v_pk_mul_f32 v[36:37], v[48:49], v[42:43] op_sel_hi:[0,1]
	v_pk_fma_f32 v[56:57], v[50:51], v[60:61], v[56:57] op_sel_hi:[0,1,1]
	v_pk_fma_f32 v[36:37], v[50:51], v[38:39], v[36:37] op_sel_hi:[0,1,1]
	v_pk_fma_f32 v[56:57], v[44:45], v[58:59], v[56:57] op_sel_hi:[0,1,1]
	v_pk_fma_f32 v[36:37], v[44:45], v[40:41], v[36:37] op_sel_hi:[0,1,1]
	v_pk_add_f32 v[56:57], v[46:47], v[56:57] op_sel_hi:[0,1]
	v_pk_add_f32 v[52:53], v[46:47], v[52:53] op_sel_hi:[0,1]
	v_pk_add_f32 v[40:41], v[46:47], v[36:37] op_sel_hi:[0,1]
	v_cvt_pk_bf16_f32 v36, v56, v57
	v_cvt_pk_bf16_f32 v37, v52, v53
	v_cvt_pk_bf16_f32 v38, v54, v55
	v_cvt_pk_bf16_f32 v39, v40, v41
	ds_write_b128 v199, v[36:39]
	s_waitcnt lgkmcnt(0)
	s_barrier
	ds_read_b128 v[36:39], v187
	ds_read_b128 v[40:43], v186
	s_waitcnt lgkmcnt(1)
	v_pk_mov_b32 v[50:51], v[36:37], v[38:39] op_sel:[1,0]
	s_waitcnt lgkmcnt(0)
	v_pk_mov_b32 v[48:49], v[42:43], v[36:37] op_sel:[1,0]
	v_perm_b32 v44, v43, v36, s47
	v_perm_b32 v45, v36, v37, s47
	ds_write_b128 v175, v[48:51] offset:16512
	v_perm_b32 v50, v42, v43, s47
	ds_write_b128 v175, v[36:39]
	v_perm_b32 v46, v37, v38, s47
	v_perm_b32 v47, v38, v39, s47
	v_mov_b32_e32 v54, v36
	v_mov_b32_e32 v55, v37
	v_perm_b32 v36, v41, v42, s47
	v_mov_b32_e32 v37, v50
	v_mov_b32_e32 v38, v44
	v_mov_b32_e32 v39, v45
	ds_write_b128 v175, v[36:39] offset:41280
	v_mov_b32_e32 v39, v36
	v_lshl_add_u64 v[36:37], v[136:137], 0, s[30:31]
	ds_write_b128 v175, v[44:47] offset:8256
	v_mov_b32_e32 v51, v44
	v_mov_b32_e32 v52, v45
	v_mov_b32_e32 v53, v46
	v_pk_mov_b32 v[46:47], v[40:41], v[42:43] op_sel:[1,0]
	v_perm_b32 v38, v40, v41, s47
	v_mov_b32_e32 v40, v50
	v_mov_b32_e32 v41, v44
	v_lshl_add_u64 v[36:37], v[36:37], 0, s[16:17]
	ds_write_b128 v175, v[50:53] offset:24768
	v_mov_b32_e32 v52, v42
	v_mov_b32_e32 v53, v43
	ds_write_b128 v175, v[38:41] offset:57792
	v_lshl_add_u64 v[38:39], v[36:37], 0, v[128:129]
	ds_write_b128 v175, v[52:55] offset:33024
	ds_write_b128 v175, v[46:49] offset:49536
	s_waitcnt lgkmcnt(0)
	s_barrier
	global_load_dwordx4 v[48:51], v[38:39], off nt
	s_and_saveexec_b64 s[28:29], s[0:1]
	s_cbranch_execz .LBB0_798
	global_load_short_d16_hi v153, v[38:39], off offset:-2

.LBB0_818:
	s_waitcnt vmcnt(0)
	s_add_u32 s42, s38, s42
	s_addc_u32 s43, s39, s43
	s_waitcnt lgkmcnt(0)
	global_load_dword v60, v129, s[42:43]
	v_add_u32_e32 v122, v167, v134
	v_add_u32_e32 v121, v165, v134
	ds_read2_b64 v[62:65], v122 offset1:4
	ds_read2_b64 v[66:69], v121 offset1:4
	ds_read2_b64 v[70:73], v122 offset0:8 offset1:12
	ds_read2_b64 v[74:77], v121 offset0:8 offset1:12
	ds_read2_b64 v[84:87], v122 offset0:16 offset1:20
	ds_read2_b64 v[88:91], v121 offset0:16 offset1:20
	global_load_dword v120, v179, s[42:43]
	s_waitcnt lgkmcnt(4)
	v_lshlrev_b32_e32 v104, 16, v66
	v_and_b32_e32 v105, 0xffff0000, v66
	v_lshlrev_b32_e32 v66, 16, v67
	v_and_b32_e32 v67, 0xffff0000, v67
	v_lshlrev_b32_e32 v78, 16, v62
	v_and_b32_e32 v79, 0xffff0000, v62
	v_lshlrev_b32_e32 v62, 16, v63
	v_and_b32_e32 v63, 0xffff0000, v63
	s_waitcnt lgkmcnt(2)
	v_lshlrev_b32_e32 v204, 16, v74
	v_and_b32_e32 v205, 0xffff0000, v74
	v_lshlrev_b32_e32 v74, 16, v75
	v_and_b32_e32 v75, 0xffff0000, v75
	v_lshlrev_b32_e32 v208, 16, v76
	v_and_b32_e32 v209, 0xffff0000, v76
	v_lshlrev_b32_e32 v124, 16, v68
	v_and_b32_e32 v125, 0xffff0000, v68
	v_lshlrev_b32_e32 v68, 16, v69
	v_and_b32_e32 v69, 0xffff0000, v69
	v_lshlrev_b32_e32 v126, 16, v70
	v_and_b32_e32 v127, 0xffff0000, v70
	v_lshlrev_b32_e32 v70, 16, v71
	v_and_b32_e32 v71, 0xffff0000, v71
	v_lshlrev_b32_e32 v206, 16, v72
	v_and_b32_e32 v207, 0xffff0000, v72
	s_waitcnt lgkmcnt(0)
	v_lshlrev_b32_e32 v216, 16, v90
	v_and_b32_e32 v217, 0xffff0000, v90
	v_lshlrev_b32_e32 v106, 16, v64
	v_and_b32_e32 v107, 0xffff0000, v64
	v_lshlrev_b32_e32 v64, 16, v65
	v_and_b32_e32 v65, 0xffff0000, v65
	v_lshlrev_b32_e32 v76, 16, v77
	v_and_b32_e32 v77, 0xffff0000, v77
	v_lshlrev_b32_e32 v212, 16, v88
	v_and_b32_e32 v213, 0xffff0000, v88
	v_lshlrev_b32_e32 v88, 16, v89
	v_and_b32_e32 v89, 0xffff0000, v89
	v_lshlrev_b32_e32 v214, 16, v86
	v_and_b32_e32 v215, 0xffff0000, v86
	v_lshlrev_b32_e32 v72, 16, v73
	v_and_b32_e32 v73, 0xffff0000, v73
	v_lshlrev_b32_e32 v210, 16, v84
	v_and_b32_e32 v211, 0xffff0000, v84
	v_lshlrev_b32_e32 v84, 16, v85
	v_and_b32_e32 v85, 0xffff0000, v85
	s_waitcnt vmcnt(1)
	v_pk_fma_f32 v[104:105], v[60:61], v[104:105], v[116:117] op_sel_hi:[0,1,1]
	v_pk_fma_f32 v[66:67], v[60:61], v[66:67], v[118:119] op_sel_hi:[0,1,1]
	v_pk_fma_f32 v[74:75], v[60:61], v[74:75], v[98:99] op_sel_hi:[0,1,1]
	v_pk_fma_f32 v[98:99], v[60:61], v[208:209], v[108:109] op_sel_hi:[0,1,1]
	v_pk_mul_f32 v[78:79], v[104:105], v[78:79]
	v_pk_mul_f32 v[62:63], v[66:67], v[62:63]
	v_pk_fma_f32 v[100:101], v[60:61], v[124:125], v[100:101] op_sel_hi:[0,1,1]
	v_pk_fma_f32 v[68:69], v[60:61], v[68:69], v[102:103] op_sel_hi:[0,1,1]
	v_pk_fma_f32 v[96:97], v[60:61], v[204:205], v[96:97] op_sel_hi:[0,1,1]
	v_pk_mul_f32 v[70:71], v[74:75], v[70:71]
	v_pk_mul_f32 v[74:75], v[98:99], v[206:207]
	v_cvt_pk_bf16_f32 v78, v78, v79
	v_cvt_pk_bf16_f32 v79, v62, v63
	v_pk_fma_f32 v[62:63], v[60:61], v[216:217], v[92:93] op_sel_hi:[0,1,1]
	v_pk_fma_f32 v[76:77], v[60:61], v[76:77], v[110:111] op_sel_hi:[0,1,1]
	v_pk_fma_f32 v[102:103], v[60:61], v[212:213], v[112:113] op_sel_hi:[0,1,1]
	v_pk_fma_f32 v[88:89], v[60:61], v[88:89], v[114:115] op_sel_hi:[0,1,1]
	v_pk_mul_f32 v[66:67], v[100:101], v[106:107]
	v_pk_mul_f32 v[64:65], v[68:69], v[64:65]
	v_pk_mul_f32 v[68:69], v[96:97], v[126:127]
	v_cvt_pk_bf16_f32 v97, v70, v71
	v_cvt_pk_bf16_f32 v70, v74, v75
	v_pk_mul_f32 v[74:75], v[62:63], v[214:215]
	v_lshlrev_b32_e32 v62, 16, v91
	v_and_b32_e32 v63, 0xffff0000, v91
	v_pk_mul_f32 v[72:73], v[76:77], v[72:73]
	v_pk_mul_f32 v[76:77], v[102:103], v[210:211]
	v_pk_mul_f32 v[84:85], v[88:89], v[84:85]
	v_cvt_pk_bf16_f32 v88, v66, v67
	v_cvt_pk_bf16_f32 v96, v68, v69
	v_lshlrev_b32_e32 v66, 16, v87
	v_and_b32_e32 v67, 0xffff0000, v87
	v_pk_fma_f32 v[68:69], v[60:61], v[62:63], v[94:95] op_sel_hi:[0,1,1]
	v_cvt_pk_bf16_f32 v71, v72, v73
	v_cvt_pk_bf16_f32 v72, v76, v77
	v_pk_mul_f32 v[76:77], v[68:69], v[66:67]
	ds_read2_b64 v[66:69], v121 offset0:24 offset1:28
	v_cvt_pk_bf16_f32 v89, v64, v65
	ds_read2_b64 v[62:65], v122 offset0:24 offset1:28
	v_cvt_pk_bf16_f32 v73, v84, v85
	v_cvt_pk_bf16_f32 v74, v74, v75
	s_waitcnt lgkmcnt(1)
	v_lshlrev_b32_e32 v84, 16, v66
	v_and_b32_e32 v85, 0xffff0000, v66
	v_cvt_pk_bf16_f32 v75, v76, v77
	s_waitcnt lgkmcnt(0)
	v_lshlrev_b32_e32 v76, 16, v62
	v_and_b32_e32 v77, 0xffff0000, v62
	v_pk_fma_f32 v[80:81], v[60:61], v[84:85], v[80:81] op_sel_hi:[0,1,1]
	v_lshlrev_b32_e32 v66, 16, v67
	v_and_b32_e32 v67, 0xffff0000, v67
	v_pk_mul_f32 v[76:77], v[80:81], v[76:77]
	v_lshlrev_b32_e32 v62, 16, v63
	v_and_b32_e32 v63, 0xffff0000, v63
	v_pk_fma_f32 v[66:67], v[60:61], v[66:67], v[82:83] op_sel_hi:[0,1,1]
	v_pk_mul_f32 v[62:63], v[66:67], v[62:63]
	v_cvt_pk_bf16_f32 v66, v76, v77
	v_lshlrev_b32_e32 v76, 16, v68
	v_and_b32_e32 v77, 0xffff0000, v68
	v_cvt_pk_bf16_f32 v67, v62, v63
	v_lshlrev_b32_e32 v62, 16, v64
	v_and_b32_e32 v63, 0xffff0000, v64
	v_pk_fma_f32 v[56:57], v[60:61], v[76:77], v[56:57] op_sel_hi:[0,1,1]
	v_pk_mul_f32 v[56:57], v[56:57], v[62:63]
	v_lshlrev_b32_e32 v62, 16, v65
	v_and_b32_e32 v63, 0xffff0000, v65
	v_lshlrev_b32_e32 v64, 16, v69
	v_and_b32_e32 v65, 0xffff0000, v69
	v_pk_fma_f32 v[58:59], v[60:61], v[64:65], v[58:59] op_sel_hi:[0,1,1]
	v_pk_mul_f32 v[58:59], v[58:59], v[62:63]
	v_cvt_pk_bf16_f32 v56, v56, v57
	v_cvt_pk_bf16_f32 v57, v58, v59
	s_barrier
	ds_write2_b64 v182, v[78:79], v[88:89] offset1:4
	ds_write2_b64 v182, v[96:97], v[70:71] offset0:8 offset1:12
	ds_write2_b64 v182, v[72:73], v[74:75] offset0:16 offset1:20
	ds_write2_b64 v182, v[66:67], v[56:57] offset0:24 offset1:28
	ds_write_b128 v176, v[52:55]
	s_and_saveexec_b64 s[28:29], s[4:5]
	v_mov_b32_e32 v52, s46
	ds_write_b128 v52, v[200:203]
	s_or_b64 exec, exec, s[28:29]
	global_load_dword v57, v183, s[36:37]
	global_load_dword v56, v184, s[36:37]
	global_load_dword v54, v185, s[36:37]
	global_load_dword v52, v183, s[40:41]
	v_and_b32_e32 v64, 0xffff0000, v49
	v_lshlrev_b32_e32 v58, 16, v48
	v_and_b32_e32 v61, 0xffff0000, v51
	v_and_b32_e32 v63, 16, v51
	v_and_b32_e32 v62, 0xffff0000, v50
	v_lshlrev_b32_e32 v51, 16, v51
	v_and_b32_e32 v65, 16, v50
	v_lshlrev_b32_e32 v67, 16, v50
	v_and_b32_e32 v48, 0xffff0000, v48
	v_lshlrev_b32_e32 v49, 16, v49
	v_and_b32_e32 v74, 0xffff0000, v45
	v_mov_b32_e32 v66, v64
	v_lshlrev_b32_e32 v68, 16, v44
	v_and_b32_e32 v71, 0xffff0000, v47
	v_and_b32_e32 v73, 16, v47
	v_and_b32_e32 v72, 0xffff0000, v46
	v_lshlrev_b32_e32 v47, 16, v47
	v_and_b32_e32 v75, 16, v46
	v_lshlrev_b32_e32 v77, 16, v46
	v_and_b32_e32 v44, 0xffff0000, v44
	v_lshlrev_b32_e32 v45, 16, v45
	v_mov_b32_e32 v50, v62
	v_mov_b32_e32 v60, v51
	v_mov_b32_e32 v152, v48
	v_pk_mov_b32 v[64:65], v[48:49], v[64:65] op_sel:[1,0]
	v_mov_b32_e32 v76, v74
	v_pk_mov_b32 v[62:63], v[66:67], v[62:63] op_sel:[1,0]
	v_and_b32_e32 v59, 0xffff0000, v43
	v_mov_b32_e32 v146, v61
	v_mov_b32_e32 v46, v72
	v_mov_b32_e32 v70, v47
	v_mov_b32_e32 v158, v44
	v_pk_mov_b32 v[74:75], v[44:45], v[74:75] op_sel:[1,0]
	v_pk_mov_b32 v[72:73], v[76:77], v[72:73] op_sel:[1,0]
	v_lshlrev_b32_e32 v69, 16, v43
	v_mov_b32_e32 v154, v71
	v_lshlrev_b32_e32 v78, 16, v40
	v_and_b32_e32 v40, 0xffff0000, v40
	v_mov_b32_e32 v156, v40
	v_and_b32_e32 v81, 16, v43
	v_and_b32_e32 v80, 0xffff0000, v42
	v_lshlrev_b32_e32 v43, 16, v42
	v_mov_b32_e32 v150, v59
	s_add_i32 s15, s15, 1
	s_add_i32 s2, s34, 0x81
	s_cmp_lt_u32 s15, s54
	s_cselect_b32 s34, s2, 0x100000
	s_cmpk_gt_i32 s34, 0x47f
	s_waitcnt vmcnt(3)
	v_mov_b32_e32 v84, v57
	s_waitcnt vmcnt(2)
	v_pk_mul_f32 v[82:83], v[152:153], v[56:57]
	v_pk_mul_f32 v[64:65], v[56:57], v[64:65] op_sel_hi:[0,1]
	v_pk_mul_f32 v[62:63], v[56:57], v[62:63] op_sel_hi:[0,1]
	v_pk_mul_f32 v[60:61], v[56:57], v[60:61] op_sel_hi:[0,1]
	v_pk_mul_f32 v[86:87], v[158:159], v[56:57]
	v_pk_mul_f32 v[74:75], v[56:57], v[74:75] op_sel_hi:[0,1]
	v_pk_mul_f32 v[72:73], v[56:57], v[72:73] op_sel_hi:[0,1]
	v_pk_mul_f32 v[70:71], v[56:57], v[70:71] op_sel_hi:[0,1]
	v_pk_fma_f32 v[82:83], v[56:57], v[58:59], v[82:83] op_sel:[0,0,1] op_sel_hi:[1,0,0]
	v_pk_fma_f32 v[64:65], v[84:85], v[48:49], v[64:65] op_sel_hi:[0,1,1]
	v_pk_fma_f32 v[62:63], v[84:85], v[66:67], v[62:63] op_sel_hi:[0,1,1]
	v_pk_fma_f32 v[60:61], v[84:85], v[50:51], v[60:61] op_sel_hi:[0,1,1]
	v_pk_fma_f32 v[86:87], v[56:57], v[68:69], v[86:87] op_sel:[0,0,1] op_sel_hi:[1,0,0]
	v_pk_fma_f32 v[74:75], v[84:85], v[44:45], v[74:75] op_sel_hi:[0,1,1]
	v_pk_fma_f32 v[72:73], v[84:85], v[76:77], v[72:73] op_sel_hi:[0,1,1]
	v_pk_fma_f32 v[70:71], v[84:85], v[46:47], v[70:71] op_sel_hi:[0,1,1]
	s_waitcnt vmcnt(1)
	v_pk_fma_f32 v[48:49], v[54:55], v[48:49], v[82:83] op_sel_hi:[0,1,1]
	v_pk_fma_f32 v[64:65], v[54:55], v[66:67], v[64:65] op_sel_hi:[0,1,1]
	v_pk_fma_f32 v[50:51], v[54:55], v[50:51], v[62:63] op_sel_hi:[0,1,1]
	v_pk_fma_f32 v[60:61], v[54:55], v[146:147], v[60:61] op_sel_hi:[0,1,1]
	v_pk_fma_f32 v[44:45], v[54:55], v[44:45], v[86:87] op_sel_hi:[0,1,1]
	v_pk_fma_f32 v[62:63], v[54:55], v[76:77], v[74:75] op_sel_hi:[0,1,1]
	v_pk_fma_f32 v[46:47], v[54:55], v[46:47], v[72:73] op_sel_hi:[0,1,1]
	v_pk_fma_f32 v[66:67], v[54:55], v[154:155], v[70:71] op_sel_hi:[0,1,1]
	s_waitcnt vmcnt(0)
	v_pk_add_f32 v[48:49], v[52:53], v[48:49] op_sel_hi:[0,1]
	v_pk_add_f32 v[64:65], v[52:53], v[64:65] op_sel_hi:[0,1]
	v_pk_add_f32 v[50:51], v[52:53], v[50:51] op_sel_hi:[0,1]
	v_pk_add_f32 v[60:61], v[52:53], v[60:61] op_sel_hi:[0,1]
	v_pk_add_f32 v[70:71], v[52:53], v[44:45] op_sel_hi:[0,1]
	v_pk_add_f32 v[62:63], v[52:53], v[62:63] op_sel_hi:[0,1]
	v_pk_add_f32 v[72:73], v[52:53], v[46:47] op_sel_hi:[0,1]
	v_pk_add_f32 v[66:67], v[52:53], v[66:67] op_sel_hi:[0,1]
	v_cvt_pk_bf16_f32 v44, v48, v49
	v_cvt_pk_bf16_f32 v45, v64, v65
	v_cvt_pk_bf16_f32 v46, v50, v51
	v_cvt_pk_bf16_f32 v47, v60, v61
	v_cvt_pk_bf16_f32 v48, v70, v71
	v_cvt_pk_bf16_f32 v49, v62, v63
	v_cvt_pk_bf16_f32 v50, v72, v73
	v_cvt_pk_bf16_f32 v51, v66, v67
	ds_write_b128 v142, v[44:47]
	ds_write_b128 v148, v[48:51]
	v_and_b32_e32 v45, 16, v42
	v_and_b32_e32 v44, 0xffff0000, v41
	v_lshlrev_b32_e32 v41, 16, v41
	v_mov_b32_e32 v42, v44
	v_pk_mul_f32 v[46:47], v[156:157], v[56:57]
	v_pk_mov_b32 v[44:45], v[40:41], v[44:45] op_sel:[1,0]
	v_pk_fma_f32 v[46:47], v[56:57], v[78:79], v[46:47] op_sel:[0,0,1] op_sel_hi:[1,0,0]
	v_pk_mul_f32 v[44:45], v[56:57], v[44:45] op_sel_hi:[0,1]
	v_pk_fma_f32 v[46:47], v[54:55], v[40:41], v[46:47] op_sel_hi:[0,1,1]
	v_pk_fma_f32 v[40:41], v[84:85], v[40:41], v[44:45] op_sel_hi:[0,1,1]
	v_pk_fma_f32 v[40:41], v[54:55], v[42:43], v[40:41] op_sel_hi:[0,1,1]
	v_pk_add_f32 v[44:45], v[52:53], v[40:41] op_sel_hi:[0,1]
	v_pk_mov_b32 v[40:41], v[42:43], v[80:81] op_sel:[1,0]
	v_mov_b32_e32 v68, v80
	v_pk_mul_f32 v[40:41], v[56:57], v[40:41] op_sel_hi:[0,1]
	v_pk_fma_f32 v[40:41], v[84:85], v[42:43], v[40:41] op_sel_hi:[0,1,1]
	v_mov_b32_e32 v58, v69
	v_pk_fma_f32 v[40:41], v[54:55], v[68:69], v[40:41] op_sel_hi:[0,1,1]
	v_pk_add_f32 v[42:43], v[52:53], v[40:41] op_sel_hi:[0,1]
	v_pk_mul_f32 v[40:41], v[56:57], v[58:59] op_sel_hi:[0,1]
	v_pk_fma_f32 v[40:41], v[84:85], v[68:69], v[40:41] op_sel_hi:[0,1,1]
	v_pk_fma_f32 v[40:41], v[54:55], v[150:151], v[40:41] op_sel_hi:[0,1,1]
	v_pk_add_f32 v[46:47], v[52:53], v[46:47] op_sel_hi:[0,1]
	v_pk_add_f32 v[48:49], v[52:53], v[40:41] op_sel_hi:[0,1]
	v_cvt_pk_bf16_f32 v40, v46, v47
	v_cvt_pk_bf16_f32 v41, v44, v45
	v_cvt_pk_bf16_f32 v42, v42, v43
	v_cvt_pk_bf16_f32 v43, v48, v49
	ds_write_b128 v142, v[40:43] offset:16448
	v_lshlrev_b32_e32 v40, 16, v36
	v_and_b32_e32 v36, 0xffff0000, v36
	v_and_b32_e32 v49, 16, v38
	v_and_b32_e32 v48, 0xffff0000, v37
	v_lshlrev_b32_e32 v37, 16, v37
	v_mov_b32_e32 v148, v36
	v_and_b32_e32 v43, 0xffff0000, v39
	v_and_b32_e32 v45, 16, v39
	v_and_b32_e32 v44, 0xffff0000, v38
	v_lshlrev_b32_e32 v47, 16, v39
	v_lshlrev_b32_e32 v39, 16, v38
	v_mov_b32_e32 v38, v48
	v_pk_mul_f32 v[50:51], v[148:149], v[56:57]
	v_pk_mov_b32 v[48:49], v[36:37], v[48:49] op_sel:[1,0]
	v_pk_fma_f32 v[40:41], v[56:57], v[40:41], v[50:51] op_sel:[0,0,1] op_sel_hi:[1,0,0]
	v_pk_mul_f32 v[48:49], v[56:57], v[48:49] op_sel_hi:[0,1]
	v_pk_fma_f32 v[40:41], v[54:55], v[36:37], v[40:41] op_sel_hi:[0,1,1]
	v_pk_fma_f32 v[36:37], v[84:85], v[36:37], v[48:49] op_sel_hi:[0,1,1]
	v_pk_fma_f32 v[36:37], v[54:55], v[38:39], v[36:37] op_sel_hi:[0,1,1]
	v_pk_add_f32 v[48:49], v[52:53], v[36:37] op_sel_hi:[0,1]
	v_pk_mov_b32 v[36:37], v[38:39], v[44:45] op_sel:[1,0]
	v_mov_b32_e32 v46, v44
	v_pk_mul_f32 v[36:37], v[56:57], v[36:37] op_sel_hi:[0,1]
	v_pk_fma_f32 v[36:37], v[84:85], v[38:39], v[36:37] op_sel_hi:[0,1,1]
	v_mov_b32_e32 v42, v47
	v_pk_fma_f32 v[36:37], v[54:55], v[46:47], v[36:37] op_sel_hi:[0,1,1]
	v_pk_add_f32 v[38:39], v[52:53], v[36:37] op_sel_hi:[0,1]
	v_pk_mul_f32 v[36:37], v[56:57], v[42:43] op_sel_hi:[0,1]
	v_pk_fma_f32 v[36:37], v[84:85], v[46:47], v[36:37] op_sel_hi:[0,1,1]
	v_mov_b32_e32 v142, v43
	v_pk_fma_f32 v[36:37], v[54:55], v[142:143], v[36:37] op_sel_hi:[0,1,1]
	v_pk_add_f32 v[40:41], v[52:53], v[40:41] op_sel_hi:[0,1]
	v_pk_add_f32 v[42:43], v[52:53], v[36:37] op_sel_hi:[0,1]
	v_cvt_pk_bf16_f32 v36, v40, v41
	v_cvt_pk_bf16_f32 v37, v48, v49
	v_cvt_pk_bf16_f32 v38, v38, v39
	v_cvt_pk_bf16_f32 v39, v42, v43
	ds_write_b128 v199, v[36:39]
	s_waitcnt lgkmcnt(0)
	s_barrier
	ds_read_b128 v[36:39], v186
	ds_read_b128 v[40:43], v187
	s_waitcnt lgkmcnt(0)
	v_perm_b32 v44, v39, v40, s47
	v_perm_b32 v45, v40, v41, s47
	v_perm_b32 v46, v41, v42, s47
	v_pk_mov_b32 v[48:49], v[38:39], v[40:41] op_sel:[1,0]
	v_pk_mov_b32 v[50:51], v[40:41], v[42:43] op_sel:[1,0]
	ds_write_b128 v175, v[40:43]
	v_perm_b32 v47, v42, v43, s47
	ds_write_b128 v175, v[48:51] offset:16512
	v_perm_b32 v50, v38, v39, s47
	v_mov_b32_e32 v51, v44
	v_mov_b32_e32 v52, v45
	v_mov_b32_e32 v53, v46
	v_mov_b32_e32 v54, v40
	v_perm_b32 v40, v37, v38, s47
	ds_write_b128 v175, v[44:47] offset:8256
	ds_write_b128 v175, v[50:53] offset:24768
	v_mov_b32_e32 v52, v38
	v_mov_b32_e32 v53, v39
	v_mov_b32_e32 v55, v41
	v_mov_b32_e32 v41, v50
	v_mov_b32_e32 v42, v44
	v_mov_b32_e32 v43, v45
	v_pk_mov_b32 v[46:47], v[36:37], v[38:39] op_sel:[1,0]
	v_perm_b32 v36, v36, v37, s47
	v_mov_b32_e32 v37, v40
	v_mov_b32_e32 v38, v50
	v_mov_b32_e32 v39, v44
	ds_write_b128 v175, v[52:55] offset:33024
	ds_write_b128 v175, v[40:43] offset:41280
	ds_write_b128 v175, v[46:49] offset:49536
	ds_write_b128 v175, v[36:39] offset:57792
	s_waitcnt lgkmcnt(0)
	s_barrier
	s_cbranch_scc1 .LBB0_854
	s_add_i32 s12, s34, 0xffffff80
	s_ashr_i32 s13, s12, 31
	s_lshl_b64 s[28:29], s[12:13], 13
	s_lshl_b64 s[12:13], s[12:13], 15
	v_lshl_add_u64 v[0:1], v[138:139], 0, s[28:29]
	v_lshl_add_u64 v[16:17], v[136:137], 0, s[12:13]
	v_lshl_add_u64 v[18:19], v[16:17], 0, v[128:129]
	global_load_dwordx4 v[0:3], v[0:1], off
	s_nop 0
	global_load_dwordx4 v[4:7], v[18:19], off nt
	v_mov_b32_e32 v226, 0
	v_mov_b32_e32 v218, 0
	s_and_saveexec_b64 s[28:29], s[0:1]
	s_cbranch_execz .LBB0_823
	global_load_ushort v218, v[18:19], off offset:-2
